# stacked: pa/pd/out conversion moved to the up2 tail, norm x prefetch, DeltaNet conv rows loaded in one batch
# baseline (speedup 1.0000x reference)
.LBB0_324:
	s_or_b64 exec, exec, s[8:9]
	v_add_u32_e32 v0, 3, v58
	v_lshl_add_u64 v[12:13], v[56:57], 0, s[6:7]
	s_mov_b64 s[8:9], 0x3000
	v_ashrrev_i32_e32 v1, 31, v0
	v_lshl_add_u64 v[4:5], v[12:13], 0, s[8:9]
	v_add_co_u32_e32 v6, vcc, s75, v12
	s_mov_b64 s[8:9], 0x6000
	v_lshlrev_b64 v[0:1], 8, v[0:1]
	v_addc_co_u32_e32 v7, vcc, 0, v13, vcc
	v_lshl_add_u64 v[8:9], v[12:13], 0, s[8:9]
	s_movk_i32 s8, 0x6000
	v_lshl_add_u64 v[0:1], v[46:47], 0, v[0:1]
	v_add_co_u32_e32 v10, vcc, s8, v12
	global_load_dwordx4 v[88:91], v[0:1], off
	v_add_u32_e32 v142, 4, v58
	v_ashrrev_i32_e32 v143, 31, v142
	v_lshlrev_b64 v[142:143], 8, v[142:143]
	v_lshl_add_u64 v[142:143], v[46:47], 0, v[142:143]
	global_load_dwordx4 v[150:153], v[142:143], off
	v_add_u32_e32 v142, 5, v58
	v_ashrrev_i32_e32 v143, 31, v142
	v_lshlrev_b64 v[142:143], 8, v[142:143]
	v_lshl_add_u64 v[142:143], v[46:47], 0, v[142:143]
	global_load_dwordx4 v[146:149], v[142:143], off
	v_add_u32_e32 v142, 6, v58
	v_ashrrev_i32_e32 v143, 31, v142
	v_lshlrev_b64 v[142:143], 8, v[142:143]
	v_lshl_add_u64 v[142:143], v[46:47], 0, v[142:143]
	global_load_dwordx4 v[142:145], v[142:143], off
	s_nop 0
	global_load_dwordx4 v[0:3], v[12:13], off offset:16
	global_load_dwordx4 v[16:19], v[12:13], off
	v_addc_co_u32_e32 v11, vcc, 0, v13, vcc
	s_mov_b32 s8, 0x9000
	v_add_co_u32_e32 v14, vcc, s8, v12
	global_load_dwordx4 v[20:23], v[6:7], off
	s_nop 0
	global_load_dwordx4 v[4:7], v[4:5], off offset:16
	v_addc_co_u32_e32 v15, vcc, 0, v13, vcc
	global_load_dwordx4 v[24:27], v[10:11], off
	s_nop 0
	global_load_dwordx4 v[8:11], v[8:9], off offset:16
	s_mov_b64 s[8:9], 0x9000
	global_load_dwordx4 v[28:31], v[14:15], off
	v_lshl_add_u64 v[12:13], v[12:13], 0, s[8:9]
	global_load_dwordx4 v[12:15], v[12:13], off offset:16
	s_waitcnt vmcnt(0)
	v_lshlrev_b32_e32 v78, 16, v36
	v_and_b32_e32 v79, 0xffff0000, v36
	v_lshlrev_b32_e32 v86, 16, v37
	v_and_b32_e32 v87, 0xffff0000, v37
	v_lshlrev_b32_e32 v36, 16, v32
	v_and_b32_e32 v37, 0xffff0000, v32
	v_lshlrev_b32_e32 v32, 16, v33
	v_and_b32_e32 v33, 0xffff0000, v33
	v_lshlrev_b32_e32 v74, 16, v40
	v_and_b32_e32 v75, 0xffff0000, v40
	v_lshlrev_b32_e32 v72, 16, v41
	v_and_b32_e32 v73, 0xffff0000, v41
	v_lshlrev_b32_e32 v82, 16, v38
	v_and_b32_e32 v83, 0xffff0000, v38
	v_lshlrev_b32_e32 v76, 16, v39
	v_and_b32_e32 v77, 0xffff0000, v39
	v_lshlrev_b32_e32 v38, 16, v34
	v_and_b32_e32 v39, 0xffff0000, v34
	v_lshlrev_b32_e32 v70, 16, v42
	v_and_b32_e32 v71, 0xffff0000, v42
	v_lshlrev_b32_e32 v68, 16, v43
	v_and_b32_e32 v69, 0xffff0000, v43
	s_cmp_lt_i32 s10, 1
	s_mov_b64 s[8:9], -1
	v_pk_fma_f32 v[38:39], v[0:1], v[38:39], 0 op_sel_hi:[1,1,0]
	v_pk_fma_f32 v[36:37], v[16:17], v[36:37], 0 op_sel_hi:[1,1,0]
	v_pk_fma_f32 v[32:33], v[18:19], v[32:33], 0 op_sel_hi:[1,1,0]
	v_lshlrev_b32_e32 v66, 16, v88
	v_and_b32_e32 v67, 0xffff0000, v88
	v_lshlrev_b32_e32 v64, 16, v89
	v_pk_fma_f32 v[36:37], v[20:21], v[78:79], v[36:37]
	v_pk_fma_f32 v[32:33], v[22:23], v[86:87], v[32:33]
	v_and_b32_e32 v65, 0xffff0000, v89
	v_pk_fma_f32 v[36:37], v[24:25], v[74:75], v[36:37]
	v_pk_fma_f32 v[32:33], v[26:27], v[72:73], v[32:33]
	v_pk_fma_f32 v[38:39], v[4:5], v[82:83], v[38:39]
	v_pk_fma_f32 v[36:37], v[28:29], v[66:67], v[36:37]
	v_pk_fma_f32 v[32:33], v[30:31], v[64:65], v[32:33]
	v_mul_f32_e32 v34, 0xbfb8aa3b, v36
	v_mul_f32_e32 v40, 0xbfb8aa3b, v37
	v_mul_f32_e32 v41, 0xbfb8aa3b, v32
	v_exp_f32_e32 v34, v34
	v_exp_f32_e32 v40, v40
	v_lshlrev_b32_e32 v62, 16, v90
	v_and_b32_e32 v63, 0xffff0000, v90
	v_pk_fma_f32 v[38:39], v[8:9], v[70:71], v[38:39]
	v_exp_f32_e32 v41, v41
	v_pk_fma_f32 v[38:39], v[12:13], v[62:63], v[38:39]
	v_mul_f32_e32 v42, 0xbfb8aa3b, v33
	v_mul_f32_e32 v43, 0xbfb8aa3b, v38
	v_exp_f32_e32 v42, v42
	v_exp_f32_e32 v80, v43
	v_add_f32_e32 v34, 1.0, v34
	v_add_f32_e32 v43, 1.0, v40
	v_add_f32_e32 v81, 1.0, v41
	v_rcp_f32_e32 v40, v34
	v_rcp_f32_e32 v41, v43
	v_add_f32_e32 v84, 1.0, v42
	v_rcp_f32_e32 v43, v84
	v_lshlrev_b32_e32 v60, 16, v91
	v_pk_mul_f32 v[84:85], v[36:37], v[40:41]
	v_lshlrev_b32_e32 v36, 16, v35
	v_and_b32_e32 v37, 0xffff0000, v35
	v_pk_fma_f32 v[36:37], v[2:3], v[36:37], 0 op_sel_hi:[1,1,0]
	v_and_b32_e32 v61, 0xffff0000, v91
	v_pk_fma_f32 v[36:37], v[6:7], v[76:77], v[36:37]
	v_rcp_f32_e32 v42, v81
	v_pk_fma_f32 v[36:37], v[10:11], v[68:69], v[36:37]
	v_mul_f32_e32 v59, 0xbfb8aa3b, v39
	v_pk_fma_f32 v[36:37], v[14:15], v[60:61], v[36:37]
	v_exp_f32_e32 v59, v59
	v_mul_f32_e32 v35, 0xbfb8aa3b, v36
	v_exp_f32_e32 v41, v35
	v_mul_f32_e32 v35, 0xbfb8aa3b, v37
	v_add_f32_e32 v34, 1.0, v80
	v_pk_mul_f32 v[80:81], v[32:33], v[42:43]
	v_exp_f32_e32 v42, v35
	v_add_f32_e32 v40, 1.0, v59
	v_rcp_f32_e32 v34, v34
	v_rcp_f32_e32 v35, v40
	v_add_f32_e32 v40, 1.0, v41
	v_add_f32_e32 v41, 1.0, v42
	v_pk_mul_f32 v[32:33], v[84:85], v[84:85]
	v_rcp_f32_e32 v40, v40
	v_rcp_f32_e32 v41, v41
	v_pk_mul_f32 v[42:43], v[80:81], v[80:81]
	v_add_f32_e32 v32, v32, v33
	v_pk_mul_f32 v[88:89], v[38:39], v[34:35]
	v_add_f32_e32 v32, v42, v32
	v_pk_mul_f32 v[34:35], v[88:89], v[88:89]
	v_add_f32_e32 v32, v43, v32
	v_pk_mul_f32 v[90:91], v[36:37], v[40:41]
	v_add_f32_e32 v32, v34, v32
	v_pk_mul_f32 v[36:37], v[90:91], v[90:91]
	v_add_f32_e32 v32, v35, v32
	v_add_f32_e32 v32, v36, v32
	v_add_f32_e32 v32, v37, v32
	s_nop 0
	s_nop 0
	v_add_f32_dpp v32, v32, v32 quad_perm:[1,0,3,2] row_mask:0xf bank_mask:0xf bound_ctrl:1
	s_nop 0
	s_nop 0
	v_add_f32_dpp v32, v32, v32 quad_perm:[2,3,0,1] row_mask:0xf bank_mask:0xf bound_ctrl:1
	s_nop 1
	v_add_f32_dpp v59, v32, v32 row_half_mirror row_mask:0xf bank_mask:0xf bound_ctrl:1
	s_nop 0
	s_nop 0
	s_nop 0
	s_nop 0
	s_nop 0
	s_nop 0
	s_nop 0
	s_nop 0
	s_nop 0
	s_nop 0
	s_nop 0
	v_mov_b32_dpp v92, v59 row_mirror row_mask:0xf bank_mask:0xf bound_ctrl:1
	v_add_f32_e32 v59, v59, v92
	v_add_f32_e32 v59, 0x358637bd, v59
	v_rsq_f32_e32 v92, v59
	s_cbranch_scc1 .LBB0_330
	s_cmp_lg_u32 s10, 1
	s_cbranch_scc0 .LBB0_327
	v_cvt_pk_bf16_f32 v112, v84, v85
	v_cvt_pk_bf16_f32 v113, v80, v81
	v_cvt_pk_bf16_f32 v114, v88, v89
	v_cvt_pk_bf16_f32 v115, v90, v91
	ds_write_b128 v100, v[112:115] offset:52224
	s_mov_b64 s[8:9], 0

.LBB0_332:
	s_waitcnt vmcnt(2)
	v_lshlrev_b32_e32 v84, 16, v150
	v_and_b32_e32 v85, 0xffff0000, v150
	v_lshlrev_b32_e32 v80, 16, v151
	v_and_b32_e32 v81, 0xffff0000, v151
	v_pk_fma_f32 v[150:151], v[16:17], v[78:79], 0 op_sel_hi:[1,1,0]
	v_pk_fma_f32 v[86:87], v[18:19], v[86:87], 0 op_sel_hi:[1,1,0]
	v_pk_fma_f32 v[150:151], v[20:21], v[74:75], v[150:151]
	v_pk_fma_f32 v[86:87], v[22:23], v[72:73], v[86:87]
	v_pk_fma_f32 v[150:151], v[24:25], v[66:67], v[150:151]
	v_pk_fma_f32 v[86:87], v[26:27], v[64:65], v[86:87]
	v_pk_fma_f32 v[88:89], v[28:29], v[84:85], v[150:151]
	v_pk_fma_f32 v[86:87], v[30:31], v[80:81], v[86:87]
	v_mul_f32_e32 v150, 0xbfb8aa3b, v88
	v_exp_f32_e32 v150, v150
	v_mul_f32_e32 v151, 0xbfb8aa3b, v89
	v_exp_f32_e32 v151, v151
	v_mul_f32_e32 v59, 0xbfb8aa3b, v86
	v_add_f32_e32 v150, 1.0, v150
	v_rcp_f32_e32 v90, v150
	v_add_f32_e32 v150, 1.0, v151
	v_rcp_f32_e32 v91, v150
	v_lshlrev_b32_e32 v78, 16, v152
	v_and_b32_e32 v79, 0xffff0000, v152
	v_lshlrev_b32_e32 v150, 16, v153
	v_and_b32_e32 v151, 0xffff0000, v153
	v_pk_mul_f32 v[152:153], v[88:89], v[90:91]
	v_exp_f32_e32 v59, v59
	v_mul_f32_e32 v88, 0xbfb8aa3b, v87
	v_exp_f32_e32 v91, v88
	v_pk_fma_f32 v[82:83], v[0:1], v[82:83], 0 op_sel_hi:[1,1,0]
	v_add_f32_e32 v59, 1.0, v59
	v_rcp_f32_e32 v90, v59
	v_add_f32_e32 v59, 1.0, v91
	v_rcp_f32_e32 v91, v59
	v_pk_fma_f32 v[82:83], v[4:5], v[70:71], v[82:83]
	v_pk_fma_f32 v[76:77], v[2:3], v[76:77], 0 op_sel_hi:[1,1,0]
	v_pk_fma_f32 v[82:83], v[8:9], v[62:63], v[82:83]
	v_pk_fma_f32 v[76:77], v[6:7], v[68:69], v[76:77]
	v_pk_fma_f32 v[112:113], v[12:13], v[78:79], v[82:83]
	v_pk_fma_f32 v[76:77], v[10:11], v[60:61], v[76:77]
	v_mul_f32_e32 v59, 0xbfb8aa3b, v112
	v_mul_f32_e32 v82, 0xbfb8aa3b, v113
	v_exp_f32_e32 v59, v59
	v_exp_f32_e32 v92, v82
	v_pk_mul_f32 v[82:83], v[86:87], v[90:91]
	v_pk_fma_f32 v[90:91], v[14:15], v[150:151], v[76:77]
	v_add_f32_e32 v59, 1.0, v59
	v_mul_f32_e32 v76, 0xbfb8aa3b, v90
	v_exp_f32_e32 v76, v76
	v_mul_f32_e32 v77, 0xbfb8aa3b, v91
	v_exp_f32_e32 v77, v77
	v_rcp_f32_e32 v86, v59
	v_add_f32_e32 v59, 1.0, v92
	v_rcp_f32_e32 v87, v59
	v_add_f32_e32 v59, 1.0, v76
	v_rcp_f32_e32 v114, v59
	v_add_f32_e32 v59, 1.0, v77
	v_pk_mul_f32 v[88:89], v[152:153], v[152:153]
	v_rcp_f32_e32 v115, v59
	v_pk_mul_f32 v[116:117], v[82:83], v[82:83]
	v_add_f32_e32 v59, v88, v89
	v_pk_mul_f32 v[76:77], v[112:113], v[86:87]
	v_add_f32_e32 v59, v116, v59
	v_pk_mul_f32 v[112:113], v[76:77], v[76:77]
	v_add_f32_e32 v59, v117, v59
	v_pk_mul_f32 v[86:87], v[90:91], v[114:115]
	v_add_f32_e32 v59, v112, v59
	v_pk_mul_f32 v[90:91], v[86:87], v[86:87]
	v_add_f32_e32 v59, v113, v59
	v_add_f32_e32 v59, v90, v59
	v_add_f32_e32 v59, v91, v59
	s_cmp_lt_i32 s10, 1
	s_mov_b64 s[8:9], -1
	v_add_f32_dpp v59, v59, v59 quad_perm:[1,0,3,2] row_mask:0xf bank_mask:0xf bound_ctrl:1
	s_nop 1
	v_add_f32_dpp v59, v59, v59 quad_perm:[2,3,0,1] row_mask:0xf bank_mask:0xf bound_ctrl:1
	s_nop 1
	v_add_f32_dpp v59, v59, v59 row_half_mirror row_mask:0xf bank_mask:0xf bound_ctrl:1
	s_nop 1
	v_mov_b32_dpp v88, v59 row_mirror row_mask:0xf bank_mask:0xf bound_ctrl:1
	v_add_f32_e32 v59, v59, v88
	v_add_f32_e32 v59, 0x358637bd, v59
	v_rsq_f32_e32 v88, v59
	s_cbranch_scc1 .LBB0_338
	s_cmp_lg_u32 s10, 1
	s_cbranch_scc0 .LBB0_335
	v_cvt_pk_bf16_f32 v112, v152, v153
	v_cvt_pk_bf16_f32 v113, v82, v83
	v_cvt_pk_bf16_f32 v114, v76, v77
	v_cvt_pk_bf16_f32 v115, v86, v87
	ds_write_b128 v103, v[112:115] offset:52224
	s_mov_b64 s[8:9], 0
.LBB0_335:
	s_andn2_b64 vcc, exec, s[8:9]
	s_cbranch_vccnz .LBB0_337
	ds_read_b32 v90, v102
	v_pk_mul_f32 v[112:113], v[152:153], v[88:89] op_sel_hi:[1,0]
	v_pk_mul_f32 v[114:115], v[82:83], v[88:89] op_sel_hi:[1,0]
	v_pk_mul_f32 v[116:117], v[76:77], v[88:89] op_sel_hi:[1,0]
	v_pk_mul_f32 v[132:133], v[86:87], v[88:89] op_sel_hi:[1,0]
	s_waitcnt lgkmcnt(0)
	v_pk_mul_f32 v[118:119], v[112:113], v[90:91] op_sel_hi:[1,0]
	v_pk_mul_f32 v[120:121], v[114:115], v[90:91] op_sel_hi:[1,0]
	v_pk_mul_f32 v[130:131], v[116:117], v[90:91] op_sel_hi:[1,0]
	v_pk_mul_f32 v[90:91], v[132:133], v[90:91] op_sel_hi:[1,0]
	v_cvt_pk_bf16_f32 v112, v112, v113
	v_cvt_pk_bf16_f32 v113, v114, v115
	v_cvt_pk_bf16_f32 v114, v116, v117
	v_cvt_pk_bf16_f32 v115, v132, v133
	ds_write_b128 v103, v[112:115] offset:17408
	v_cvt_pk_bf16_f32 v112, v118, v119
	v_cvt_pk_bf16_f32 v113, v120, v121
	v_cvt_pk_bf16_f32 v114, v130, v131
	v_cvt_pk_bf16_f32 v115, v90, v91
	ds_write_b128 v103, v[112:115] offset:34816

.LBB0_338:
	s_andn2_b64 vcc, exec, s[8:9]
	s_cbranch_vccnz .LBB0_340
	ds_read_b32 v90, v104
	v_pk_mul_f32 v[152:153], v[152:153], v[88:89] op_sel_hi:[1,0]
	v_pk_mul_f32 v[82:83], v[82:83], v[88:89] op_sel_hi:[1,0]
	v_pk_mul_f32 v[76:77], v[76:77], v[88:89] op_sel_hi:[1,0]
	v_pk_mul_f32 v[86:87], v[86:87], v[88:89] op_sel_hi:[1,0]
	v_pk_mul_f32 v[152:153], v[152:153], s[2:3] op_sel_hi:[1,0]
	v_pk_mul_f32 v[82:83], v[82:83], s[2:3] op_sel_hi:[1,0]
	v_pk_mul_f32 v[76:77], v[76:77], s[2:3] op_sel_hi:[1,0]
	v_pk_mul_f32 v[118:119], v[86:87], s[2:3] op_sel_hi:[1,0]
	v_cvt_pk_bf16_f32 v86, v152, v153
	v_cvt_pk_bf16_f32 v87, v82, v83
	v_cvt_pk_bf16_f32 v88, v76, v77
	v_cvt_pk_bf16_f32 v89, v118, v119
	s_mov_b32 s8, s26
	ds_write_b128 v103, v[86:89]
	s_ashr_i32 s9, s8, 31
	s_waitcnt lgkmcnt(1)
	v_pk_mul_f32 v[112:113], v[152:153], v[90:91] op_sel_hi:[1,0]
	v_pk_mul_f32 v[114:115], v[82:83], v[90:91] op_sel_hi:[1,0]
	v_pk_mul_f32 v[116:117], v[76:77], v[90:91] op_sel_hi:[1,0]
	v_pk_mul_f32 v[90:91], v[118:119], v[90:91] op_sel_hi:[1,0]
	s_lshl_b64 s[8:9], s[8:9], 14
	v_cvt_pk_bf16_f32 v86, v112, v113
	v_cvt_pk_bf16_f32 v87, v114, v115
	v_cvt_pk_bf16_f32 v88, v116, v117
	v_cvt_pk_bf16_f32 v89, v90, v91
	v_lshl_add_u64 v[152:153], v[50:51], 0, s[8:9]
	global_store_dwordx4 v[152:153], v[86:89], off
.LBB0_340:
	s_waitcnt vmcnt(1)
	v_lshlrev_b32_e32 v82, 16, v146
	v_and_b32_e32 v83, 0xffff0000, v146
	v_lshlrev_b32_e32 v76, 16, v147
	v_and_b32_e32 v77, 0xffff0000, v147
	v_pk_fma_f32 v[146:147], v[16:17], v[74:75], 0 op_sel_hi:[1,1,0]
	v_pk_fma_f32 v[72:73], v[18:19], v[72:73], 0 op_sel_hi:[1,1,0]
	v_pk_fma_f32 v[146:147], v[20:21], v[66:67], v[146:147]
	v_pk_fma_f32 v[72:73], v[22:23], v[64:65], v[72:73]
	v_pk_fma_f32 v[146:147], v[24:25], v[84:85], v[146:147]
	v_pk_fma_f32 v[72:73], v[26:27], v[80:81], v[72:73]
	v_pk_fma_f32 v[74:75], v[28:29], v[82:83], v[146:147]
	v_pk_fma_f32 v[72:73], v[30:31], v[76:77], v[72:73]
	v_mul_f32_e32 v146, 0xbfb8aa3b, v74
	v_exp_f32_e32 v146, v146
	v_mul_f32_e32 v147, 0xbfb8aa3b, v75
	v_exp_f32_e32 v147, v147
	v_mul_f32_e32 v59, 0xbfb8aa3b, v72
	v_add_f32_e32 v146, 1.0, v146
	v_rcp_f32_e32 v86, v146
	v_add_f32_e32 v146, 1.0, v147
	v_rcp_f32_e32 v87, v146
	v_lshlrev_b32_e32 v152, 16, v148
	v_and_b32_e32 v153, 0xffff0000, v148
	v_lshlrev_b32_e32 v146, 16, v149
	v_and_b32_e32 v147, 0xffff0000, v149
	v_pk_mul_f32 v[148:149], v[74:75], v[86:87]
	v_exp_f32_e32 v59, v59
	v_mul_f32_e32 v74, 0xbfb8aa3b, v73
	v_exp_f32_e32 v87, v74
	v_pk_fma_f32 v[70:71], v[0:1], v[70:71], 0 op_sel_hi:[1,1,0]
	v_add_f32_e32 v59, 1.0, v59
	v_rcp_f32_e32 v86, v59
	v_add_f32_e32 v59, 1.0, v87
	v_rcp_f32_e32 v87, v59
	v_pk_fma_f32 v[70:71], v[4:5], v[62:63], v[70:71]
	v_pk_fma_f32 v[68:69], v[2:3], v[68:69], 0 op_sel_hi:[1,1,0]
	v_pk_fma_f32 v[70:71], v[8:9], v[78:79], v[70:71]
	v_pk_fma_f32 v[68:69], v[6:7], v[60:61], v[68:69]
	v_pk_fma_f32 v[88:89], v[12:13], v[152:153], v[70:71]
	v_pk_fma_f32 v[68:69], v[10:11], v[150:151], v[68:69]
	v_mul_f32_e32 v59, 0xbfb8aa3b, v88
	v_mul_f32_e32 v70, 0xbfb8aa3b, v89
	v_exp_f32_e32 v59, v59
	v_exp_f32_e32 v90, v70
	v_pk_mul_f32 v[70:71], v[72:73], v[86:87]
	v_pk_fma_f32 v[86:87], v[14:15], v[146:147], v[68:69]
	v_add_f32_e32 v59, 1.0, v59
	v_mul_f32_e32 v68, 0xbfb8aa3b, v86
	v_exp_f32_e32 v68, v68
	v_mul_f32_e32 v69, 0xbfb8aa3b, v87
	v_exp_f32_e32 v69, v69
	v_rcp_f32_e32 v72, v59
	v_add_f32_e32 v59, 1.0, v90
	v_rcp_f32_e32 v73, v59
	v_add_f32_e32 v59, 1.0, v68
	v_rcp_f32_e32 v90, v59
	v_add_f32_e32 v59, 1.0, v69
	v_pk_mul_f32 v[74:75], v[148:149], v[148:149]
	v_rcp_f32_e32 v91, v59
	v_pk_mul_f32 v[112:113], v[70:71], v[70:71]
	v_add_f32_e32 v59, v74, v75
	v_pk_mul_f32 v[68:69], v[88:89], v[72:73]
	v_add_f32_e32 v59, v112, v59
	v_pk_mul_f32 v[88:89], v[68:69], v[68:69]
	v_add_f32_e32 v59, v113, v59
	v_pk_mul_f32 v[72:73], v[86:87], v[90:91]
	v_add_f32_e32 v59, v88, v59
	v_pk_mul_f32 v[86:87], v[72:73], v[72:73]
	v_add_f32_e32 v59, v89, v59
	v_add_f32_e32 v59, v86, v59
	v_add_f32_e32 v59, v87, v59
	s_cmp_lt_i32 s10, 1
	s_mov_b64 s[8:9], -1
	v_add_f32_dpp v59, v59, v59 quad_perm:[1,0,3,2] row_mask:0xf bank_mask:0xf bound_ctrl:1
	s_nop 1
	v_add_f32_dpp v59, v59, v59 quad_perm:[2,3,0,1] row_mask:0xf bank_mask:0xf bound_ctrl:1
	s_nop 1
	v_add_f32_dpp v59, v59, v59 row_half_mirror row_mask:0xf bank_mask:0xf bound_ctrl:1
	s_nop 1
	v_mov_b32_dpp v74, v59 row_mirror row_mask:0xf bank_mask:0xf bound_ctrl:1
	v_add_f32_e32 v59, v59, v74
	v_add_f32_e32 v59, 0x358637bd, v59
	v_rsq_f32_e32 v74, v59
	s_cbranch_scc1 .LBB0_346
	s_cmp_lg_u32 s10, 1
	s_cbranch_scc0 .LBB0_343
	v_cvt_pk_bf16_f32 v86, v148, v149
	v_cvt_pk_bf16_f32 v87, v70, v71
	v_cvt_pk_bf16_f32 v88, v68, v69
	v_cvt_pk_bf16_f32 v89, v72, v73
	ds_write_b128 v106, v[86:89] offset:52224
	s_mov_b64 s[8:9], 0
.LBB0_343:
	s_andn2_b64 vcc, exec, s[8:9]
	s_cbranch_vccnz .LBB0_345
	ds_read_b32 v86, v105
	v_pk_mul_f32 v[88:89], v[148:149], v[74:75] op_sel_hi:[1,0]
	v_pk_mul_f32 v[90:91], v[70:71], v[74:75] op_sel_hi:[1,0]
	v_pk_mul_f32 v[112:113], v[68:69], v[74:75] op_sel_hi:[1,0]
	v_pk_mul_f32 v[120:121], v[72:73], v[74:75] op_sel_hi:[1,0]
	s_waitcnt lgkmcnt(0)
	v_pk_mul_f32 v[114:115], v[88:89], v[86:87] op_sel_hi:[1,0]
	v_pk_mul_f32 v[116:117], v[90:91], v[86:87] op_sel_hi:[1,0]
	v_pk_mul_f32 v[118:119], v[112:113], v[86:87] op_sel_hi:[1,0]
	v_pk_mul_f32 v[130:131], v[120:121], v[86:87] op_sel_hi:[1,0]
	v_cvt_pk_bf16_f32 v86, v88, v89
	v_cvt_pk_bf16_f32 v87, v90, v91
	v_cvt_pk_bf16_f32 v88, v112, v113
	v_cvt_pk_bf16_f32 v89, v120, v121
	ds_write_b128 v106, v[86:89] offset:17408
	v_cvt_pk_bf16_f32 v86, v114, v115
	v_cvt_pk_bf16_f32 v87, v116, v117
	v_cvt_pk_bf16_f32 v88, v118, v119
	v_cvt_pk_bf16_f32 v89, v130, v131
	ds_write_b128 v106, v[86:89] offset:34816

.LBB0_346:
	s_andn2_b64 vcc, exec, s[8:9]
	s_cbranch_vccnz .LBB0_348
	ds_read_b32 v86, v107
	v_pk_mul_f32 v[68:69], v[68:69], v[74:75] op_sel_hi:[1,0]
	v_pk_mul_f32 v[148:149], v[148:149], v[74:75] op_sel_hi:[1,0]
	v_pk_mul_f32 v[70:71], v[70:71], v[74:75] op_sel_hi:[1,0]
	v_pk_mul_f32 v[112:113], v[68:69], s[2:3] op_sel_hi:[1,0]
	v_pk_mul_f32 v[68:69], v[72:73], v[74:75] op_sel_hi:[1,0]
	v_pk_mul_f32 v[148:149], v[148:149], s[2:3] op_sel_hi:[1,0]
	v_pk_mul_f32 v[70:71], v[70:71], s[2:3] op_sel_hi:[1,0]
	v_pk_mul_f32 v[72:73], v[68:69], s[2:3] op_sel_hi:[1,0]
	s_waitcnt lgkmcnt(0)
	v_pk_mul_f32 v[90:91], v[70:71], v[86:87] op_sel_hi:[1,0]
	v_cvt_pk_bf16_f32 v68, v148, v149
	v_cvt_pk_bf16_f32 v69, v70, v71
	v_cvt_pk_bf16_f32 v70, v112, v113
	v_cvt_pk_bf16_f32 v71, v72, v73
	s_mov_b32 s8, s26
	ds_write_b128 v106, v[68:71]
	s_ashr_i32 s9, s8, 31
	v_pk_mul_f32 v[88:89], v[148:149], v[86:87] op_sel_hi:[1,0]
	v_pk_mul_f32 v[114:115], v[112:113], v[86:87] op_sel_hi:[1,0]
	v_pk_mul_f32 v[74:75], v[72:73], v[86:87] op_sel_hi:[1,0]
	s_lshl_b64 s[8:9], s[8:9], 14
	v_cvt_pk_bf16_f32 v68, v88, v89
	v_cvt_pk_bf16_f32 v69, v90, v91
	v_cvt_pk_bf16_f32 v70, v114, v115
	v_cvt_pk_bf16_f32 v71, v74, v75
	v_lshl_add_u64 v[148:149], v[52:53], 0, s[8:9]
	global_store_dwordx4 v[148:149], v[68:71], off
.LBB0_348:
	v_pk_fma_f32 v[16:17], v[16:17], v[66:67], 0 op_sel_hi:[1,1,0]
	v_pk_fma_f32 v[18:19], v[18:19], v[64:65], 0 op_sel_hi:[1,1,0]
	v_pk_fma_f32 v[16:17], v[20:21], v[84:85], v[16:17]
	s_waitcnt vmcnt(0)
	v_lshlrev_b32_e32 v20, 16, v142
	v_pk_fma_f32 v[16:17], v[24:25], v[82:83], v[16:17]
	v_and_b32_e32 v21, 0xffff0000, v142
	v_pk_fma_f32 v[16:17], v[28:29], v[20:21], v[16:17]
	v_pk_fma_f32 v[18:19], v[22:23], v[80:81], v[18:19]
	v_mul_f32_e32 v20, 0xbfb8aa3b, v16
	v_mul_f32_e32 v21, 0xbfb8aa3b, v17
	v_exp_f32_e32 v20, v20
	v_exp_f32_e32 v21, v21
	v_pk_fma_f32 v[0:1], v[0:1], v[62:63], 0 op_sel_hi:[1,1,0]
	v_pk_fma_f32 v[2:3], v[2:3], v[60:61], 0 op_sel_hi:[1,1,0]
	v_add_f32_e32 v20, 1.0, v20
	v_add_f32_e32 v21, 1.0, v21
	v_rcp_f32_e32 v20, v20
	v_rcp_f32_e32 v21, v21
	v_pk_fma_f32 v[18:19], v[26:27], v[76:77], v[18:19]
	v_pk_fma_f32 v[0:1], v[4:5], v[78:79], v[0:1]
	v_pk_fma_f32 v[2:3], v[6:7], v[150:151], v[2:3]
	v_pk_mul_f32 v[16:17], v[16:17], v[20:21]
	v_lshlrev_b32_e32 v20, 16, v143
	v_and_b32_e32 v21, 0xffff0000, v143
	v_pk_fma_f32 v[18:19], v[30:31], v[20:21], v[18:19]
	v_pk_fma_f32 v[0:1], v[8:9], v[152:153], v[0:1]
	v_lshlrev_b32_e32 v4, 16, v144
	v_and_b32_e32 v5, 0xffff0000, v144
	v_pk_fma_f32 v[2:3], v[10:11], v[146:147], v[2:3]
	v_lshlrev_b32_e32 v6, 16, v145
	v_and_b32_e32 v7, 0xffff0000, v145
	v_mul_f32_e32 v20, 0xbfb8aa3b, v18
	v_pk_fma_f32 v[4:5], v[12:13], v[4:5], v[0:1]
	v_pk_fma_f32 v[6:7], v[14:15], v[6:7], v[2:3]
	v_exp_f32_e32 v22, v20
	v_mul_f32_e32 v20, 0xbfb8aa3b, v19
	v_mul_f32_e32 v0, 0xbfb8aa3b, v4
	v_mul_f32_e32 v2, 0xbfb8aa3b, v6
	v_exp_f32_e32 v23, v20
	v_exp_f32_e32 v8, v0
	v_mul_f32_e32 v0, 0xbfb8aa3b, v5
	v_exp_f32_e32 v2, v2
	v_mul_f32_e32 v3, 0xbfb8aa3b, v7
	v_exp_f32_e32 v9, v0
	v_exp_f32_e32 v3, v3
	v_add_f32_e32 v22, 1.0, v22
	v_add_f32_e32 v23, 1.0, v23
	v_add_f32_e32 v2, 1.0, v2
	v_rcp_f32_e32 v22, v22
	v_rcp_f32_e32 v23, v23
	v_add_f32_e32 v8, 1.0, v8
	v_add_f32_e32 v9, 1.0, v9
	v_rcp_f32_e32 v10, v2
	v_add_f32_e32 v2, 1.0, v3
	v_rcp_f32_e32 v8, v8
	v_rcp_f32_e32 v9, v9
	v_rcp_f32_e32 v11, v2
	v_pk_mul_f32 v[20:21], v[16:17], v[16:17]
	v_pk_mul_f32 v[0:1], v[18:19], v[22:23]
	v_pk_mul_f32 v[2:3], v[4:5], v[8:9]
	v_pk_mul_f32 v[12:13], v[0:1], v[0:1]
	v_pk_mul_f32 v[4:5], v[6:7], v[10:11]
	v_add_f32_e32 v10, v20, v21
	v_add_f32_e32 v10, v12, v10
	v_pk_mul_f32 v[8:9], v[2:3], v[2:3]
	v_add_f32_e32 v10, v13, v10
	v_add_f32_e32 v8, v8, v10
	v_pk_mul_f32 v[6:7], v[4:5], v[4:5]
	v_add_f32_e32 v8, v9, v8
	v_add_f32_e32 v6, v6, v8
	v_add_f32_e32 v6, v7, v6
	s_cmp_lt_i32 s10, 1
	s_mov_b64 s[8:9], -1
	v_add_f32_dpp v6, v6, v6 quad_perm:[1,0,3,2] row_mask:0xf bank_mask:0xf bound_ctrl:1
	s_nop 1
	v_add_f32_dpp v6, v6, v6 quad_perm:[2,3,0,1] row_mask:0xf bank_mask:0xf bound_ctrl:1
	s_nop 1
	v_add_f32_dpp v6, v6, v6 row_half_mirror row_mask:0xf bank_mask:0xf bound_ctrl:1
	s_nop 1
	v_mov_b32_dpp v7, v6 row_mirror row_mask:0xf bank_mask:0xf bound_ctrl:1
	v_add_f32_e32 v6, v6, v7
	v_add_f32_e32 v6, 0x358637bd, v6
	v_rsq_f32_e32 v6, v6
	s_cbranch_scc1 .LBB0_354
	s_cmp_lg_u32 s10, 1
	s_cbranch_scc0 .LBB0_351
	v_cvt_pk_bf16_f32 v8, v16, v17
	v_cvt_pk_bf16_f32 v9, v0, v1
	v_cvt_pk_bf16_f32 v10, v2, v3
	v_cvt_pk_bf16_f32 v11, v4, v5
	ds_write_b128 v109, v[8:11] offset:52224
	s_mov_b64 s[8:9], 0

.LBB0_430:
	s_mov_b32 s92, 0x0
	s_mov_b32 s93, 0

.LBB0_666:
	v_readlane_b32 s4, v253, 0
	s_cmpk_lt_i32 s4, 0x80
	s_cbranch_scc1 .Lconv_ret3
	s_mov_b64 s[64:65], s[0:1]
	v_lshrrev_b32_e32 v0, 8, v154
	v_mul_u32_u24_e32 v122, 0x12000, v0
	v_mov_b32_e32 v1, v154
	s_nop 0
	v_readfirstlane_b32 s5, v1
	v_writelane_b32 v254, s4, 62
	s_lshl_b32 s6, s4, 1
	v_writelane_b32 v255, s6, 0
	v_writelane_b32 v254, s5, 63
	s_ashr_i32 s5, s5, 8
	s_add_i32 s6, s5, s6
	v_writelane_b32 v255, s5, 1
	v_writelane_b32 v254, s6, 61
	s_mov_b32 s92, 0xf8
	s_mov_b32 s93, 3
	s_branch .Lconv_entry
